# fcum q/k bound loop: second load batch issued without waiting for the first; counted vmcnt(6); loads as global_load
# baseline (speedup 1.0000x reference)
; __device__ __forceinline__ float bf2f(unsigned short h) { return __uint_as_float(((unsigned)h) << 16); }
; __device__ __forceinline__ void p5a_fcum(const Args& A, char* lds, int G) {
;     ...
;           for (int i = 0; i < 32; ++i) { const size_t m = (size_t)b * SEQL + (tid >> 3) + 64 * i; const int c8 = tid & 7; float qs = 0.f, ks2 = 0.f;
;               const bf16x8 qv = *(const bf16x8*)(P1 + m * LD1 + C1_Q + h * 64 + c8 * 8), kv = *(const bf16x8*)(P1 + m * LD1 + C1_K + h * 64 + c8 * 8);
; #pragma unroll
;               for (int e = 0; e < 8; ++e) { const float qf = bf2f((unsigned short)qv[e]), kf = bf2f((unsigned short)kv[e]); qs += qf * qf; ks2 += kf * kf; }
.LBB0_1335:
	v_lshl_add_u64 v[2:3], v[0:1], 0, s[54:55]
	v_add_co_u32_e64 v40, s[30:31], s65, v2
	v_add_co_u32_e32 v96, vcc, 0x1b00000, v2
	s_nop 0
	v_addc_co_u32_e64 v41, s[30:31], 0, v3, s[30:31]
	v_add_co_u32_e64 v44, s[30:31], s66, v2
	v_addc_co_u32_e32 v97, vcc, 0, v3, vcc
	s_nop 0
	v_addc_co_u32_e64 v45, s[30:31], 0, v3, s[30:31]
	v_add_co_u32_e64 v48, s[30:31], s67, v2
	s_add_u32 s54, s54, 0x700000
	s_nop 0
	v_addc_co_u32_e64 v49, s[30:31], 0, v3, s[30:31]
	v_add_co_u32_e64 v52, s[30:31], s68, v2
	s_addc_u32 s55, s55, 0
	s_nop 0
	v_addc_co_u32_e64 v53, s[30:31], 0, v3, s[30:31]
	v_add_co_u32_e64 v56, s[30:31], s69, v2
	s_cmp_lg_u32 s54, 0x1c00000
	s_nop 0
	v_addc_co_u32_e64 v57, s[30:31], 0, v3, s[30:31]
	v_add_co_u32_e64 v60, s[30:31], s71, v2
	s_nop 1
	v_addc_co_u32_e64 v61, s[30:31], 0, v3, s[30:31]
	v_add_co_u32_e64 v64, s[30:31], s72, v2
	s_nop 1
	v_addc_co_u32_e64 v65, s[30:31], 0, v3, s[30:31]
	v_add_co_u32_e64 v68, s[30:31], s73, v2
	s_nop 1
	v_addc_co_u32_e64 v69, s[30:31], 0, v3, s[30:31]
	v_add_co_u32_e64 v72, s[30:31], s74, v2
	s_nop 1
	v_addc_co_u32_e64 v73, s[30:31], 0, v3, s[30:31]
	v_add_co_u32_e64 v76, s[30:31], s75, v2
	s_nop 1
	v_addc_co_u32_e64 v77, s[30:31], 0, v3, s[30:31]
	v_add_co_u32_e64 v80, s[30:31], s76, v2
	global_load_dwordx4 v[40:43], v[40:41], off
	s_nop 0
	global_load_dwordx4 v[44:47], v[44:45], off
	s_nop 0
	global_load_dwordx4 v[48:51], v[48:49], off
	s_nop 0
	global_load_dwordx4 v[52:55], v[52:53], off
	s_nop 0
	global_load_dwordx4 v[56:59], v[56:57], off
	s_nop 0
	global_load_dwordx4 v[60:63], v[60:61], off
	s_nop 0
	global_load_dwordx4 v[64:67], v[64:65], off
	s_nop 0
	global_load_dwordx4 v[68:71], v[68:69], off
	s_nop 0
	global_load_dwordx4 v[72:75], v[72:73], off
	s_nop 0
	global_load_dwordx4 v[76:79], v[76:77], off
	v_addc_co_u32_e64 v81, s[30:31], 0, v3, s[30:31]
	v_add_co_u32_e64 v84, s[30:31], s77, v2
	v_addc_co_u32_e64 v85, s[30:31], 0, v3, s[30:31]
	v_add_co_u32_e64 v88, s[30:31], s78, v2
	s_nop 0
	v_addc_co_u32_e64 v89, s[30:31], 0, v3, s[30:31]
	v_add_co_u32_e64 v92, s[30:31], s79, v2
	v_add_co_u32_e32 v2, vcc, 0x1b01000, v2
	s_nop 0
	v_addc_co_u32_e64 v93, s[30:31], 0, v3, s[30:31]
	global_load_dwordx4 v[80:83], v[80:81], off
	s_nop 0
	global_load_dwordx4 v[84:87], v[84:85], off
	s_nop 0
	global_load_dwordx4 v[88:91], v[88:89], off
	s_nop 0
	global_load_dwordx4 v[92:95], v[92:93], off
	v_addc_co_u32_e32 v3, vcc, 0, v3, vcc
	global_load_dwordx4 v[96:99], v[96:97], off
	s_nop 0
	global_load_dwordx4 v[100:103], v[2:3], off
	s_waitcnt vmcnt(6)
	v_and_b32_e32 v107, 0xffff0000, v41
	v_and_b32_e32 v105, 0xffff0000, v44
	v_and_b32_e32 v3, 0xffff0000, v40
	v_lshlrev_b32_e32 v2, 16, v40
	v_lshlrev_b32_e32 v104, 16, v44
	v_lshlrev_b32_e32 v106, 16, v41
	v_and_b32_e32 v109, 0xffff0000, v46
	v_lshlrev_b32_e32 v108, 16, v46
	v_and_b32_e32 v111, 0xffff0000, v43
	v_lshlrev_b32_e32 v110, 16, v43
	v_and_b32_e32 v113, 0xffff0000, v52
	v_lshlrev_b32_e32 v112, 16, v52
	v_and_b32_e32 v115, 0xffff0000, v49
	v_lshlrev_b32_e32 v114, 16, v49
	v_and_b32_e32 v117, 0xffff0000, v54
	v_lshlrev_b32_e32 v116, 16, v54
	v_and_b32_e32 v119, 0xffff0000, v51
	v_lshlrev_b32_e32 v118, 16, v51
	v_and_b32_e32 v121, 0xffff0000, v60
	v_lshlrev_b32_e32 v120, 16, v60
	v_and_b32_e32 v123, 0xffff0000, v57
	v_lshlrev_b32_e32 v122, 16, v57
	v_and_b32_e32 v125, 0xffff0000, v62
	v_lshlrev_b32_e32 v124, 16, v62
	v_and_b32_e32 v127, 0xffff0000, v59
	v_lshlrev_b32_e32 v126, 16, v59
	v_and_b32_e32 v129, 0xffff0000, v68
	v_lshlrev_b32_e32 v128, 16, v68
	v_and_b32_e32 v131, 0xffff0000, v65
	v_lshlrev_b32_e32 v130, 16, v65
	v_and_b32_e32 v133, 0xffff0000, v70
	v_lshlrev_b32_e32 v132, 16, v70
	v_and_b32_e32 v135, 0xffff0000, v67
	v_lshlrev_b32_e32 v134, 16, v67
	v_and_b32_e32 v137, 0xffff0000, v76
	v_lshlrev_b32_e32 v136, 16, v76
	v_and_b32_e32 v139, 0xffff0000, v73
	v_lshlrev_b32_e32 v138, 16, v73
	v_and_b32_e32 v141, 0xffff0000, v78
	v_lshlrev_b32_e32 v140, 16, v78
	v_and_b32_e32 v143, 0xffff0000, v75
	v_lshlrev_b32_e32 v142, 16, v75
	v_and_b32_e32 v41, 0xffff0000, v45
	v_lshlrev_b32_e32 v40, 16, v45
	v_and_b32_e32 v45, 0xffff0000, v42
	v_lshlrev_b32_e32 v44, 16, v42
	v_and_b32_e32 v43, 0xffff0000, v47
	v_lshlrev_b32_e32 v42, 16, v47
	v_and_b32_e32 v47, 0xffff0000, v48
	v_lshlrev_b32_e32 v46, 16, v48
	v_and_b32_e32 v49, 0xffff0000, v53
	v_lshlrev_b32_e32 v48, 16, v53
	v_and_b32_e32 v53, 0xffff0000, v50
	v_lshlrev_b32_e32 v52, 16, v50
	v_and_b32_e32 v51, 0xffff0000, v55
	v_lshlrev_b32_e32 v50, 16, v55
	v_and_b32_e32 v55, 0xffff0000, v56
	v_lshlrev_b32_e32 v54, 16, v56
	v_and_b32_e32 v57, 0xffff0000, v61
	v_lshlrev_b32_e32 v56, 16, v61
	v_and_b32_e32 v61, 0xffff0000, v58
	v_lshlrev_b32_e32 v60, 16, v58
	v_and_b32_e32 v59, 0xffff0000, v63
	v_lshlrev_b32_e32 v58, 16, v63
	v_and_b32_e32 v63, 0xffff0000, v64
	v_lshlrev_b32_e32 v62, 16, v64
	v_and_b32_e32 v65, 0xffff0000, v69
	v_lshlrev_b32_e32 v64, 16, v69
	v_and_b32_e32 v69, 0xffff0000, v66
	v_lshlrev_b32_e32 v68, 16, v66
	v_and_b32_e32 v67, 0xffff0000, v71
	v_lshlrev_b32_e32 v66, 16, v71
	v_and_b32_e32 v71, 0xffff0000, v72
	v_lshlrev_b32_e32 v70, 16, v72
	v_and_b32_e32 v73, 0xffff0000, v77
	s_waitcnt vmcnt(0) lgkmcnt(0)
; __device__ __forceinline__ float bf2f(unsigned short h) { return __uint_as_float(((unsigned)h) << 16); }
; template <int CTRL> __device__ __forceinline__ float dppf(float old, float src) { return __builtin_bit_cast(float, __builtin_amdgcn_update_dpp(__builtin_bit_cast(int, old), __builtin_bit_cast(int, src), CTRL, 0xF, 0xF, false)); }
; __device__ __forceinline__ void p5a_fcum(const Args& A, char* lds, int G) {
;     ...
;               for (int e = 0; e < 8; ++e) { const float qf = bf2f((unsigned short)qv[e]), kf = bf2f((unsigned short)kv[e]); qs += qf * qf; ks2 += kf * kf; }
;               qs += dppf<0xB1>(qs, qs); qs += dppf<0x4E>(qs, qs); qs += dppf<0x141>(qs, qs); ks2 += dppf<0xB1>(ks2, ks2); ks2 += dppf<0x4E>(ks2, ks2); ks2 += dppf<0x141>(ks2, ks2);
	v_and_b32_e32 v147, 0xffff0000, v81
	v_and_b32_e32 v145, 0xffff0000, v84
	v_lshlrev_b32_e32 v144, 16, v84
	v_lshlrev_b32_e32 v146, 16, v81
	v_and_b32_e32 v149, 0xffff0000, v86
	v_lshlrev_b32_e32 v148, 16, v86
	v_and_b32_e32 v151, 0xffff0000, v83
	v_lshlrev_b32_e32 v150, 16, v83
	v_and_b32_e32 v153, 0xffff0000, v92
	v_lshlrev_b32_e32 v152, 16, v92
	v_and_b32_e32 v155, 0xffff0000, v89
	v_lshlrev_b32_e32 v154, 16, v89
	v_and_b32_e32 v157, 0xffff0000, v94
	v_lshlrev_b32_e32 v156, 16, v94
	v_and_b32_e32 v159, 0xffff0000, v91
	v_lshlrev_b32_e32 v158, 16, v91
	v_lshlrev_b32_e32 v72, 16, v77
	v_and_b32_e32 v77, 0xffff0000, v74
	v_lshlrev_b32_e32 v76, 16, v74
	v_and_b32_e32 v75, 0xffff0000, v79
	v_lshlrev_b32_e32 v74, 16, v79
	v_and_b32_e32 v79, 0xffff0000, v80
	v_lshlrev_b32_e32 v78, 16, v80
	v_and_b32_e32 v81, 0xffff0000, v85
	v_lshlrev_b32_e32 v80, 16, v85
	v_and_b32_e32 v85, 0xffff0000, v82
	v_lshlrev_b32_e32 v84, 16, v82
	v_and_b32_e32 v83, 0xffff0000, v87
	v_lshlrev_b32_e32 v82, 16, v87
	v_and_b32_e32 v87, 0xffff0000, v88
	v_lshlrev_b32_e32 v86, 16, v88
	v_and_b32_e32 v89, 0xffff0000, v93
	v_lshlrev_b32_e32 v88, 16, v93
	v_and_b32_e32 v93, 0xffff0000, v90
	v_lshlrev_b32_e32 v92, 16, v90
	v_and_b32_e32 v91, 0xffff0000, v95
	v_lshlrev_b32_e32 v90, 16, v95
	v_and_b32_e32 v95, 0xffff0000, v96
	v_lshlrev_b32_e32 v94, 16, v96
	v_and_b32_e32 v161, 0xffff0000, v97
	v_lshlrev_b32_e32 v160, 16, v97
	v_and_b32_e32 v97, 0xffff0000, v98
	v_lshlrev_b32_e32 v96, 16, v98
	v_and_b32_e32 v163, 0xffff0000, v99
	v_lshlrev_b32_e32 v162, 16, v99
	v_pk_mul_f32 v[2:3], v[2:3], v[2:3]
	v_pk_mul_f32 v[98:99], v[104:105], v[104:105]
	v_pk_mul_f32 v[104:105], v[106:107], v[106:107]
	v_pk_mul_f32 v[106:107], v[108:109], v[108:109]
	v_pk_mul_f32 v[108:109], v[110:111], v[110:111]
	v_pk_mul_f32 v[110:111], v[112:113], v[112:113]
	v_pk_mul_f32 v[112:113], v[114:115], v[114:115]
	v_pk_mul_f32 v[114:115], v[116:117], v[116:117]
	v_pk_mul_f32 v[116:117], v[118:119], v[118:119]
	v_pk_mul_f32 v[118:119], v[120:121], v[120:121]
	v_pk_mul_f32 v[120:121], v[122:123], v[122:123]
	v_pk_mul_f32 v[122:123], v[124:125], v[124:125]
	v_pk_mul_f32 v[124:125], v[126:127], v[126:127]
	v_pk_mul_f32 v[126:127], v[128:129], v[128:129]
	v_pk_mul_f32 v[128:129], v[130:131], v[130:131]
	v_pk_mul_f32 v[130:131], v[132:133], v[132:133]
	v_pk_mul_f32 v[132:133], v[134:135], v[134:135]
	v_pk_mul_f32 v[134:135], v[136:137], v[136:137]
	v_pk_mul_f32 v[136:137], v[138:139], v[138:139]
	v_pk_mul_f32 v[138:139], v[140:141], v[140:141]
	v_pk_mul_f32 v[140:141], v[142:143], v[142:143]
	v_pk_mul_f32 v[142:143], v[144:145], v[144:145]
	v_pk_mul_f32 v[144:145], v[146:147], v[146:147]
	v_pk_mul_f32 v[146:147], v[148:149], v[148:149]
	v_pk_mul_f32 v[148:149], v[150:151], v[150:151]
	v_pk_mul_f32 v[150:151], v[152:153], v[152:153]
	v_pk_mul_f32 v[152:153], v[154:155], v[154:155]
	v_pk_mul_f32 v[154:155], v[156:157], v[156:157]
	v_pk_mul_f32 v[156:157], v[158:159], v[158:159]
	v_and_b32_e32 v159, 0xffff0000, v100
	v_lshlrev_b32_e32 v158, 16, v100
	v_pk_mul_f32 v[46:47], v[46:47], v[46:47]
	v_pk_mul_f32 v[54:55], v[54:55], v[54:55]
	v_pk_mul_f32 v[62:63], v[62:63], v[62:63]
	v_pk_mul_f32 v[70:71], v[70:71], v[70:71]
	v_pk_mul_f32 v[78:79], v[78:79], v[78:79]
	v_pk_mul_f32 v[86:87], v[86:87], v[86:87]
	v_pk_mul_f32 v[94:95], v[94:95], v[94:95]
	v_and_b32_e32 v165, 0xffff0000, v101
	v_lshlrev_b32_e32 v164, 16, v101
	v_add_f32_e32 v15, v2, v3
	v_pk_mul_f32 v[2:3], v[158:159], v[158:159]
	v_pk_mul_f32 v[40:41], v[40:41], v[40:41]
	v_pk_mul_f32 v[48:49], v[48:49], v[48:49]
	v_pk_mul_f32 v[56:57], v[56:57], v[56:57]
	v_pk_mul_f32 v[64:65], v[64:65], v[64:65]
	v_pk_mul_f32 v[72:73], v[72:73], v[72:73]
	v_pk_mul_f32 v[80:81], v[80:81], v[80:81]
	v_pk_mul_f32 v[160:161], v[160:161], v[160:161]
	v_and_b32_e32 v101, 0xffff0000, v102
	v_lshlrev_b32_e32 v100, 16, v102
	v_and_b32_e32 v167, 0xffff0000, v103
	v_lshlrev_b32_e32 v166, 16, v103
	v_add_f32_e32 v39, v98, v99
	v_add_f32_e32 v98, v46, v47
	v_add_f32_e32 v99, v110, v111
	v_add_f32_e32 v102, v54, v55
	v_add_f32_e32 v103, v118, v119
	v_add_f32_e32 v110, v62, v63
	v_add_f32_e32 v111, v126, v127
	v_add_f32_e32 v70, v70, v71
	v_add_f32_e32 v71, v134, v135
	v_add_f32_e32 v78, v78, v79
	v_add_f32_e32 v79, v142, v143
	v_add_f32_e32 v86, v86, v87
	v_pk_mul_f32 v[46:47], v[164:165], v[164:165]
	v_add_f32_e32 v94, v94, v95
	v_add_f32_e32 v2, v2, v3
	v_pk_mul_f32 v[88:89], v[88:89], v[88:89]
	v_add_f32_e32 v87, v150, v151
	v_add_f32_e32 v15, v104, v15
	v_add_f32_e32 v39, v40, v39
	v_add_f32_e32 v40, v112, v98
	v_add_f32_e32 v48, v48, v99
	v_add_f32_e32 v95, v120, v102
	v_add_f32_e32 v56, v56, v103
	v_add_f32_e32 v98, v128, v110
	v_add_f32_e32 v64, v64, v111
	v_add_f32_e32 v70, v136, v70
	v_add_f32_e32 v71, v72, v71
	v_add_f32_e32 v72, v144, v78
	v_add_f32_e32 v78, v80, v79
	v_add_f32_e32 v79, v152, v86
	v_add_f32_e32 v86, v160, v94
	v_add_f32_e32 v2, v46, v2
	v_pk_mul_f32 v[44:45], v[44:45], v[44:45]
	v_pk_mul_f32 v[52:53], v[52:53], v[52:53]
	v_pk_mul_f32 v[60:61], v[60:61], v[60:61]
	v_pk_mul_f32 v[68:69], v[68:69], v[68:69]
	v_pk_mul_f32 v[76:77], v[76:77], v[76:77]
	v_pk_mul_f32 v[84:85], v[84:85], v[84:85]
	v_pk_mul_f32 v[92:93], v[92:93], v[92:93]
	v_pk_mul_f32 v[96:97], v[96:97], v[96:97]
	v_pk_mul_f32 v[54:55], v[100:101], v[100:101]
	v_add_f32_e32 v80, v88, v87
	v_add_f32_e32 v3, v105, v15
	v_add_f32_e32 v15, v41, v39
	v_add_f32_e32 v39, v113, v40
	v_add_f32_e32 v40, v49, v48
	v_add_f32_e32 v41, v121, v95
	v_add_f32_e32 v48, v57, v56
	v_add_f32_e32 v49, v129, v98
	v_add_f32_e32 v56, v65, v64
	v_add_f32_e32 v57, v137, v70
	v_add_f32_e32 v64, v73, v71
	v_add_f32_e32 v65, v145, v72
; __device__ __forceinline__ float bf2f(unsigned short h) { return __uint_as_float(((unsigned)h) << 16); }
; template <int CTRL> __device__ __forceinline__ float dppf(float old, float src) { return __builtin_bit_cast(float, __builtin_amdgcn_update_dpp(__builtin_bit_cast(int, old), __builtin_bit_cast(int, src), CTRL, 0xF, 0xF, false)); }
; __device__ __forceinline__ void p5a_fcum(const Args& A, char* lds, int G) {
;     ...
;               for (int e = 0; e < 8; ++e) { const float qf = bf2f((unsigned short)qv[e]), kf = bf2f((unsigned short)kv[e]); qs += qf * qf; ks2 += kf * kf; }
;               qs += dppf<0xB1>(qs, qs); qs += dppf<0x4E>(qs, qs); qs += dppf<0x141>(qs, qs); ks2 += dppf<0xB1>(ks2, ks2); ks2 += dppf<0x4E>(ks2, ks2); ks2 += dppf<0x141>(ks2, ks2);
	v_add_f32_e32 v70, v81, v78
	v_add_f32_e32 v71, v153, v79
	v_add_f32_e32 v73, v161, v86
	v_add_f32_e32 v2, v47, v2
	v_add_f32_e32 v72, v89, v80
	v_add_f32_e32 v3, v44, v3
	v_add_f32_e32 v15, v106, v15
	v_add_f32_e32 v39, v52, v39
	v_add_f32_e32 v40, v114, v40
	v_add_f32_e32 v41, v60, v41
	v_add_f32_e32 v44, v122, v48
	v_add_f32_e32 v46, v68, v49
	v_add_f32_e32 v48, v130, v56
	v_add_f32_e32 v49, v76, v57
	v_add_f32_e32 v52, v138, v64
	v_add_f32_e32 v56, v84, v65
	v_add_f32_e32 v57, v146, v70
	v_add_f32_e32 v60, v92, v71
	v_add_f32_e32 v65, v96, v73
	v_add_f32_e32 v2, v54, v2
	v_pk_mul_f32 v[42:43], v[42:43], v[42:43]
	v_pk_mul_f32 v[50:51], v[50:51], v[50:51]
	v_pk_mul_f32 v[162:163], v[162:163], v[162:163]
	v_pk_mul_f32 v[62:63], v[166:167], v[166:167]
	v_add_f32_e32 v64, v154, v72
	v_add_f32_e32 v3, v45, v3
	v_add_f32_e32 v15, v107, v15
	v_add_f32_e32 v39, v53, v39
	v_add_f32_e32 v40, v115, v40
	v_add_f32_e32 v45, v69, v46
	v_add_f32_e32 v46, v131, v48
	v_add_f32_e32 v48, v139, v52
	v_add_f32_e32 v52, v147, v57
	v_add_f32_e32 v53, v93, v60
	v_add_f32_e32 v57, v97, v65
	v_add_f32_e32 v2, v55, v2
	v_pk_mul_f32 v[58:59], v[58:59], v[58:59]
	v_pk_mul_f32 v[66:67], v[66:67], v[66:67]
	v_pk_mul_f32 v[74:75], v[74:75], v[74:75]
	v_pk_mul_f32 v[82:83], v[82:83], v[82:83]
	v_pk_mul_f32 v[90:91], v[90:91], v[90:91]
	v_add_f32_e32 v41, v61, v41
	v_add_f32_e32 v44, v123, v44
	v_add_f32_e32 v47, v77, v49
	v_add_f32_e32 v49, v85, v56
	v_add_f32_e32 v56, v155, v64
	v_add_f32_e32 v3, v108, v3
	v_add_f32_e32 v15, v42, v15
	v_add_f32_e32 v40, v50, v40
	v_add_f32_e32 v50, v156, v53
	v_add_f32_e32 v53, v162, v57
	v_add_f32_e32 v2, v62, v2
	v_add_f32_e32 v39, v116, v39
	v_add_f32_e32 v41, v124, v41
	v_add_f32_e32 v42, v58, v44
	v_add_f32_e32 v44, v132, v45
	v_add_f32_e32 v45, v66, v46
	v_add_f32_e32 v46, v140, v47
	v_add_f32_e32 v47, v74, v48
	v_add_f32_e32 v48, v148, v49
	v_add_f32_e32 v49, v82, v52
	v_add_f32_e32 v52, v90, v56
	v_add_f32_e32 v3, v109, v3
	v_add_f32_e32 v15, v43, v15
	v_add_f32_e32 v40, v51, v40
	v_add_f32_e32 v51, v163, v53
	v_add_f32_e32 v2, v63, v2
	v_add_f32_e32 v39, v117, v39
	v_add_f32_e32 v41, v125, v41
	v_add_f32_e32 v42, v59, v42
	v_add_f32_e32 v43, v133, v44
	v_add_f32_e32 v44, v67, v45
	v_add_f32_e32 v45, v141, v46
	v_add_f32_e32 v46, v75, v47
	v_add_f32_e32 v47, v149, v48
	v_add_f32_e32 v48, v83, v49
	v_add_f32_e32 v49, v157, v50
	v_add_f32_e32 v50, v91, v52
	v_mov_b32_e32 v52, v3
	v_mov_b32_e32 v53, v15
	v_mov_b32_e32 v63, v51
	v_mov_b32_e32 v67, v2
	v_mov_b32_e32 v54, v39
	v_mov_b32_e32 v55, v40
	v_mov_b32_e32 v56, v41
	v_mov_b32_e32 v57, v42
	v_mov_b32_e32 v66, v50
	v_mov_b32_dpp v52, v52 quad_perm:[1,0,3,2] row_mask:0xf bank_mask:0xf
	v_mov_b32_dpp v53, v53 quad_perm:[1,0,3,2] row_mask:0xf bank_mask:0xf
	v_mov_b32_dpp v63, v63 quad_perm:[1,0,3,2] row_mask:0xf bank_mask:0xf
	v_mov_b32_dpp v67, v67 quad_perm:[1,0,3,2] row_mask:0xf bank_mask:0xf
	v_mov_b32_e32 v58, v43
	v_mov_b32_e32 v59, v44
	v_mov_b32_e32 v60, v45
	v_mov_b32_e32 v61, v46
	v_mov_b32_dpp v54, v54 quad_perm:[1,0,3,2] row_mask:0xf bank_mask:0xf
	v_mov_b32_dpp v55, v55 quad_perm:[1,0,3,2] row_mask:0xf bank_mask:0xf
	v_mov_b32_dpp v56, v56 quad_perm:[1,0,3,2] row_mask:0xf bank_mask:0xf
	v_mov_b32_dpp v57, v57 quad_perm:[1,0,3,2] row_mask:0xf bank_mask:0xf
	v_mov_b32_dpp v66, v66 quad_perm:[1,0,3,2] row_mask:0xf bank_mask:0xf
	v_add_f32_e32 v3, v3, v52
	v_add_f32_e32 v15, v15, v53
	v_add_f32_e32 v51, v51, v63
	v_add_f32_e32 v2, v2, v67
	v_mov_b32_e32 v62, v47
	v_mov_b32_e32 v64, v48
	v_mov_b32_e32 v65, v49
	v_mov_b32_dpp v58, v58 quad_perm:[1,0,3,2] row_mask:0xf bank_mask:0xf
	v_mov_b32_dpp v59, v59 quad_perm:[1,0,3,2] row_mask:0xf bank_mask:0xf
	v_mov_b32_dpp v60, v60 quad_perm:[1,0,3,2] row_mask:0xf bank_mask:0xf
	v_mov_b32_dpp v61, v61 quad_perm:[1,0,3,2] row_mask:0xf bank_mask:0xf
	v_add_f32_e32 v39, v39, v54
	v_add_f32_e32 v40, v40, v55
	v_add_f32_e32 v41, v41, v56
	v_add_f32_e32 v42, v42, v57
	v_add_f32_e32 v50, v50, v66
	v_mov_b32_e32 v52, v3
	v_mov_b32_e32 v53, v15
	v_mov_b32_e32 v66, v51
	v_mov_b32_e32 v67, v2
	v_mov_b32_dpp v62, v62 quad_perm:[1,0,3,2] row_mask:0xf bank_mask:0xf
	v_mov_b32_dpp v64, v64 quad_perm:[1,0,3,2] row_mask:0xf bank_mask:0xf
	v_mov_b32_dpp v65, v65 quad_perm:[1,0,3,2] row_mask:0xf bank_mask:0xf
	v_add_f32_e32 v43, v43, v58
	v_add_f32_e32 v44, v44, v59
	v_add_f32_e32 v45, v45, v60
	v_add_f32_e32 v46, v46, v61
	v_mov_b32_e32 v54, v39
	v_mov_b32_e32 v55, v40
	v_mov_b32_e32 v56, v41
	v_mov_b32_e32 v57, v42
	v_mov_b32_dpp v52, v52 quad_perm:[2,3,0,1] row_mask:0xf bank_mask:0xf
	v_mov_b32_dpp v53, v53 quad_perm:[2,3,0,1] row_mask:0xf bank_mask:0xf
	v_mov_b32_dpp v66, v66 quad_perm:[2,3,0,1] row_mask:0xf bank_mask:0xf
	v_mov_b32_dpp v67, v67 quad_perm:[2,3,0,1] row_mask:0xf bank_mask:0xf
	v_add_f32_e32 v47, v47, v62
	v_add_f32_e32 v48, v48, v64
	v_add_f32_e32 v49, v49, v65
	v_mov_b32_e32 v58, v43
	v_mov_b32_e32 v59, v44
	v_mov_b32_e32 v60, v45
	v_mov_b32_e32 v61, v46
; template <int CTRL> __device__ __forceinline__ float dppf(float old, float src) { return __builtin_bit_cast(float, __builtin_amdgcn_update_dpp(__builtin_bit_cast(int, old), __builtin_bit_cast(int, src), CTRL, 0xF, 0xF, false)); }
; __device__ __forceinline__ void p5a_fcum(const Args& A, char* lds, int G) {
;     ...
;               qs += dppf<0xB1>(qs, qs); qs += dppf<0x4E>(qs, qs); qs += dppf<0x141>(qs, qs); ks2 += dppf<0xB1>(ks2, ks2); ks2 += dppf<0x4E>(ks2, ks2); ks2 += dppf<0x141>(ks2, ks2);
;               qm = fmaxf(qm, qs); km = fmaxf(km, ks2); }
; #pragma unroll
;           for (int o = 1; o < 64; o <<= 1) { qm = fmaxf(qm, __shfl_xor(qm, o)); km = fmaxf(km, __shfl_xor(km, o)); }
;           __syncthreads();
;           if (lane == 0) { wtot[16 + wave] = qm; wtot[32 + wave] = km; }
	v_mov_b32_dpp v54, v54 quad_perm:[2,3,0,1] row_mask:0xf bank_mask:0xf
	v_mov_b32_dpp v55, v55 quad_perm:[2,3,0,1] row_mask:0xf bank_mask:0xf
	v_mov_b32_dpp v56, v56 quad_perm:[2,3,0,1] row_mask:0xf bank_mask:0xf
	v_mov_b32_dpp v57, v57 quad_perm:[2,3,0,1] row_mask:0xf bank_mask:0xf
	v_add_f32_e32 v3, v3, v52
	v_add_f32_e32 v15, v15, v53
	v_add_f32_e32 v51, v51, v66
	v_add_f32_e32 v2, v2, v67
	v_mov_b32_e32 v62, v47
	v_mov_b32_e32 v63, v48
	v_mov_b32_e32 v64, v49
	v_mov_b32_e32 v65, v50
	v_mov_b32_dpp v58, v58 quad_perm:[2,3,0,1] row_mask:0xf bank_mask:0xf
	v_mov_b32_dpp v59, v59 quad_perm:[2,3,0,1] row_mask:0xf bank_mask:0xf
	v_mov_b32_dpp v60, v60 quad_perm:[2,3,0,1] row_mask:0xf bank_mask:0xf
	v_mov_b32_dpp v61, v61 quad_perm:[2,3,0,1] row_mask:0xf bank_mask:0xf
	v_add_f32_e32 v39, v39, v54
	v_add_f32_e32 v40, v40, v55
	v_add_f32_e32 v41, v41, v56
	v_add_f32_e32 v42, v42, v57
	v_mov_b32_e32 v52, v3
	v_mov_b32_e32 v53, v15
	v_mov_b32_e32 v66, v51
	v_mov_b32_e32 v67, v2
	v_mov_b32_dpp v62, v62 quad_perm:[2,3,0,1] row_mask:0xf bank_mask:0xf
	v_mov_b32_dpp v63, v63 quad_perm:[2,3,0,1] row_mask:0xf bank_mask:0xf
	v_mov_b32_dpp v64, v64 quad_perm:[2,3,0,1] row_mask:0xf bank_mask:0xf
	v_mov_b32_dpp v65, v65 quad_perm:[2,3,0,1] row_mask:0xf bank_mask:0xf
	v_add_f32_e32 v43, v43, v58
	v_add_f32_e32 v44, v44, v59
	v_add_f32_e32 v45, v45, v60
	v_add_f32_e32 v46, v46, v61
	v_mov_b32_e32 v54, v39
	v_mov_b32_e32 v55, v40
	v_mov_b32_e32 v56, v41
	v_mov_b32_e32 v57, v42
	v_mov_b32_dpp v52, v52 row_half_mirror row_mask:0xf bank_mask:0xf
	v_mov_b32_dpp v53, v53 row_half_mirror row_mask:0xf bank_mask:0xf
	v_mov_b32_dpp v66, v66 row_half_mirror row_mask:0xf bank_mask:0xf
	v_mov_b32_dpp v67, v67 row_half_mirror row_mask:0xf bank_mask:0xf
	v_add_f32_e32 v47, v47, v62
	v_add_f32_e32 v48, v48, v63
	v_add_f32_e32 v49, v49, v64
	v_add_f32_e32 v50, v50, v65
	v_mov_b32_e32 v58, v43
	v_mov_b32_e32 v59, v44
	v_mov_b32_e32 v60, v45
	v_mov_b32_e32 v61, v46
	v_mov_b32_dpp v54, v54 row_half_mirror row_mask:0xf bank_mask:0xf
	v_mov_b32_dpp v55, v55 row_half_mirror row_mask:0xf bank_mask:0xf
	v_mov_b32_dpp v56, v56 row_half_mirror row_mask:0xf bank_mask:0xf
	v_mov_b32_dpp v57, v57 row_half_mirror row_mask:0xf bank_mask:0xf
	v_add_f32_e32 v3, v3, v52
	v_add_f32_e32 v15, v15, v53
	v_add_f32_e32 v51, v51, v66
	v_add_f32_e32 v2, v2, v67
	v_mov_b32_e32 v62, v47
	v_mov_b32_e32 v63, v48
	v_mov_b32_e32 v64, v49
	v_mov_b32_e32 v65, v50
	v_mov_b32_dpp v58, v58 row_half_mirror row_mask:0xf bank_mask:0xf
	v_mov_b32_dpp v59, v59 row_half_mirror row_mask:0xf bank_mask:0xf
	v_mov_b32_dpp v60, v60 row_half_mirror row_mask:0xf bank_mask:0xf
	v_mov_b32_dpp v61, v61 row_half_mirror row_mask:0xf bank_mask:0xf
	v_add_f32_e32 v39, v39, v54
	v_add_f32_e32 v40, v40, v55
	v_add_f32_e32 v41, v41, v56
	v_add_f32_e32 v42, v42, v57
	v_max3_f32 v3, v14, v51, v3
	v_max3_f32 v2, v11, v2, v15
	v_mov_b32_dpp v62, v62 row_half_mirror row_mask:0xf bank_mask:0xf
	v_mov_b32_dpp v63, v63 row_half_mirror row_mask:0xf bank_mask:0xf
	v_mov_b32_dpp v64, v64 row_half_mirror row_mask:0xf bank_mask:0xf
	v_mov_b32_dpp v65, v65 row_half_mirror row_mask:0xf bank_mask:0xf
	v_add_f32_e32 v43, v43, v58
	v_add_f32_e32 v44, v44, v59
	v_add_f32_e32 v45, v45, v60
	v_add_f32_e32 v46, v46, v61
	v_max3_f32 v3, v3, v39, v41
	v_max3_f32 v2, v2, v40, v42
	v_add_f32_e32 v47, v47, v62
	v_add_f32_e32 v48, v48, v63
	v_add_f32_e32 v49, v49, v64
	v_add_f32_e32 v50, v50, v65
	v_max3_f32 v3, v3, v43, v45
	v_max3_f32 v2, v2, v44, v46
	v_max3_f32 v14, v3, v47, v49
	v_max3_f32 v11, v2, v48, v50
	s_cbranch_scc1 .LBB0_1335
	ds_bpermute_b32 v0, v26, v14
	ds_bpermute_b32 v1, v26, v11
	v_max_f32_e32 v2, v14, v14
	v_max_f32_e32 v3, v11, v11
	s_waitcnt lgkmcnt(0)
	v_max_f32_e32 v0, v0, v0
	v_max_f32_e32 v1, v1, v1
	v_max_f32_e32 v0, v2, v0
	v_max_f32_e32 v1, v3, v1
	ds_bpermute_b32 v2, v27, v0
	ds_bpermute_b32 v3, v27, v1
	s_barrier
	s_waitcnt lgkmcnt(0)
	v_max_f32_e32 v2, v2, v2
	v_max_f32_e32 v3, v3, v3
	v_max_f32_e32 v0, v0, v2
	v_max_f32_e32 v1, v1, v3
	ds_bpermute_b32 v2, v28, v0
	ds_bpermute_b32 v3, v28, v1
	s_waitcnt lgkmcnt(1)
	v_max_f32_e32 v2, v2, v2
	s_waitcnt lgkmcnt(0)
	v_max_f32_e32 v3, v3, v3
	v_max_f32_e32 v0, v0, v2
	v_max_f32_e32 v1, v1, v3
	ds_bpermute_b32 v2, v29, v0
	ds_bpermute_b32 v3, v29, v1
	s_waitcnt lgkmcnt(1)
	v_max_f32_e32 v2, v2, v2
	s_waitcnt lgkmcnt(0)
	v_max_f32_e32 v3, v3, v3
	v_max_f32_e32 v0, v0, v2
	v_max_f32_e32 v2, v1, v3
	ds_bpermute_b32 v1, v30, v0
	ds_bpermute_b32 v3, v30, v2
	s_waitcnt lgkmcnt(1)
	v_max_f32_e32 v1, v1, v1
	s_waitcnt lgkmcnt(0)
	v_max_f32_e32 v3, v3, v3
	v_max_f32_e32 v1, v0, v1
	v_max_f32_e32 v0, v2, v3
	ds_bpermute_b32 v3, v31, v1
	ds_bpermute_b32 v2, v31, v0
	s_and_saveexec_b64 s[30:31], s[10:11]
	s_cbranch_execz .LBB0_1338
	s_waitcnt lgkmcnt(1)
	v_max_f32_e32 v3, v3, v3
	v_max_f32_e32 v1, v1, v1
	s_waitcnt lgkmcnt(0)
	v_max_f32_e32 v2, v2, v2
	v_max_f32_e32 v0, v0, v0
	v_max_f32_e32 v1, v1, v3
	v_max_f32_e32 v0, v0, v2
	ds_write2_b32 v17, v1, v0 offset0:16 offset1:32
